# plus residual epilogue of phase N (layers 0-2 fast path, 16 loads in flight; last layer keeps the original code)
# speedup vs baseline: 1.0047x; 1.0029x over previous
; __device__ __forceinline__ unsigned cvt_pk_bf16(float lo, float hi) { unsigned r; asm volatile("v_cvt_pk_bf16_f32 %0, %1, %2" : "=v"(r) : "v"(lo), "v"(hi)); return r; }
;     __device__ __forceinline__ void operator()(const f32x4 (&acc)[2][2][4][2], const Unit& u, int wr, int wc, int fr, int fq) const {
;     ...
; #pragma unroll
;         for (int ai = 0; ai < 2; ++ai)
; #pragma unroll
;             for (int m = 0; m < 4; ++m) { const int row = u.pm * BM + ai * HALF + wr * 64 + m * 16 + fr; const int b = row >= 4224 ? 1 : 0, t = row - b * 4224; float ss = 0.f;
; #pragma unroll
;                 for (int bj = 0; bj < 2; ++bj)
; #pragma unroll
;                     for (int n = 0; n < 2; ++n) { const int col = u.pn * BM + bj * HALF + wc * 32 + n * 16 + 4 * fq; float* p = H + (size_t)row * 2048 + col;
;                         const f32x4 v = *(const f32x4*)p + acc[ai][bj][m][n] * s; *(f32x4*)p = v;
;                         if (SSQ != nullptr) { typedef unsigned u32x2 __attribute__((ext_vector_type(2))); u32x2 w; w.x = cvt_pk_bf16(v[0], v[1]); w.y = cvt_pk_bf16(v[2], v[3]); *(u32x2*)(HB + (size_t)row * 2048 + col) = w;
;                             ss += (v[0] * v[0] + v[1] * v[1]) + (v[2] * v[2] + v[3] * v[3]); }
;                         if (OUT != 0ull && t >= 128) *(__attribute__((address_space(1))) f32x4*)(OUT + ((size_t)(b * 4096 + t - 128) * 2048 + col) * 4) = v; }
;                 if (SSQ != nullptr) {
;                     { float p0 = ss, p1 = ss; asm("s_nop 1\n\tv_permlane16_swap_b32 %0, %1" : "+v"(p0), "+v"(p1)); ss = p0 + p1; p0 = ss; p1 = ss; asm("s_nop 1\n\tv_permlane32_swap_b32 %0, %1" : "+v"(p0), "+v"(p1)); ss = p0 + p1; }
;                     if (fq == 0) SSQ[(size_t)row * 32 + 4 * u.pn + wc] = ss; }
;                 asm volatile("" ::: "memory"); }
.LBB0_1584:
	s_add_i32 s0, s0, s45
	v_add_u32_e32 v144, s0, v0
	s_lshl_b32 s0, s68, 8
	v_ashrrev_i32_e32 v145, 31, v144
	s_or_b32 s0, s0, s48
	v_lshl_add_u32 v142, v158, 2, s0
	s_and_b64 vcc, exec, s[16:17]
	s_cbranch_vccz .Lnepi_slow
	s_and_b64 vcc, exec, s[30:31]
	s_cbranch_vccnz .Lnepi_slow
	v_cmp_eq_u32_e32 vcc, 0, v158
	v_lshlrev_b32_e32 v159, 13, v144
	v_lshl_add_u32 v159, v142, 2, v159
	s_lshl_b32 s36, s68, 4
	s_lshl_b32 s0, s44, 2
	s_add_i32 s36, s36, s0
	v_lshl_add_u32 v160, v144, 7, s36
	global_load_dwordx4 v[182:185], v159, s[14:15]
	global_load_dwordx4 v[186:189], v159, s[14:15] offset:64
	global_load_dwordx4 v[190:193], v159, s[14:15] offset:512
	global_load_dwordx4 v[194:197], v159, s[14:15] offset:576
	v_add_u32_e32 v241, 0x20000, v159
	global_load_dwordx4 v[198:201], v241, s[14:15]
	global_load_dwordx4 v[202:205], v241, s[14:15] offset:64
	global_load_dwordx4 v[206:209], v241, s[14:15] offset:512
	global_load_dwordx4 v[210:213], v241, s[14:15] offset:576
	v_add_u32_e32 v241, 0x40000, v159
	global_load_dwordx4 v[214:217], v241, s[14:15]
	global_load_dwordx4 v[218:221], v241, s[14:15] offset:64
	global_load_dwordx4 v[222:225], v241, s[14:15] offset:512
	global_load_dwordx4 v[226:229], v241, s[14:15] offset:576
	v_add_u32_e32 v241, 0x60000, v159
	global_load_dwordx4 v[146:149], v241, s[14:15]
	global_load_dwordx4 v[150:153], v241, s[14:15] offset:64
	global_load_dwordx4 v[154:157], v241, s[14:15] offset:512
	global_load_dwordx4 v[130:133], v241, s[14:15] offset:576
	v_mov_b32_e32 v161, v159
	v_lshrrev_b32_e32 v166, 1, v161
	s_waitcnt vmcnt(12)
	v_pk_fma_f32 v[128:129], v[128:129], 0.5, v[184:185] op_sel_hi:[1,0,1]
	v_pk_fma_f32 v[126:127], v[126:127], 0.5, v[182:183] op_sel_hi:[1,0,1]
	global_store_dwordx4 v161, v[126:129], s[14:15]
	v_cvt_pk_bf16_f32 v244, v126, v127
	v_cvt_pk_bf16_f32 v245, v128, v129
	global_store_dwordx2 v166, v[244:245], s[20:21]
	v_mul_f32_e32 v167, v127, v127
	v_mul_f32_e32 v143, v126, v126
	v_mul_f32_e32 v145, v128, v128
	v_mul_f32_e32 v142, v129, v129
	v_add_f32_e32 v167, v167, v143
	v_add_f32_e32 v240, v145, v142
	v_add_f32_e32 v167, v167, v240
	v_pk_fma_f32 v[124:125], v[124:125], 0.5, v[188:189] op_sel_hi:[1,0,1]
	v_pk_fma_f32 v[122:123], v[122:123], 0.5, v[186:187] op_sel_hi:[1,0,1]
	global_store_dwordx4 v161, v[122:125], s[14:15] offset:64
	v_cvt_pk_bf16_f32 v244, v122, v123
	v_cvt_pk_bf16_f32 v245, v124, v125
	global_store_dwordx2 v166, v[244:245], s[20:21] offset:32
	v_mul_f32_e32 v169, v123, v123
	v_mul_f32_e32 v143, v122, v122
	v_mul_f32_e32 v145, v124, v124
	v_mul_f32_e32 v142, v125, v125
	v_add_f32_e32 v169, v169, v143
	v_add_f32_e32 v240, v145, v142
	v_add_f32_e32 v169, v169, v240
	v_add_f32_e32 v167, v167, v169
	v_pk_fma_f32 v[96:97], v[96:97], 0.5, v[192:193] op_sel_hi:[1,0,1]
	v_pk_fma_f32 v[94:95], v[94:95], 0.5, v[190:191] op_sel_hi:[1,0,1]
	global_store_dwordx4 v161, v[94:97], s[14:15] offset:512
	v_cvt_pk_bf16_f32 v244, v94, v95
	v_cvt_pk_bf16_f32 v245, v96, v97
	global_store_dwordx2 v166, v[244:245], s[20:21] offset:256
	v_mul_f32_e32 v169, v95, v95
	v_mul_f32_e32 v143, v94, v94
	v_mul_f32_e32 v145, v96, v96
	v_mul_f32_e32 v142, v97, v97
	v_add_f32_e32 v169, v169, v143
	v_add_f32_e32 v240, v145, v142
	v_add_f32_e32 v169, v169, v240
	v_add_f32_e32 v167, v167, v169
	v_pk_fma_f32 v[92:93], v[92:93], 0.5, v[196:197] op_sel_hi:[1,0,1]
	v_pk_fma_f32 v[90:91], v[90:91], 0.5, v[194:195] op_sel_hi:[1,0,1]
	global_store_dwordx4 v161, v[90:93], s[14:15] offset:576
	v_cvt_pk_bf16_f32 v244, v90, v91
	v_cvt_pk_bf16_f32 v245, v92, v93
	global_store_dwordx2 v166, v[244:245], s[20:21] offset:288
	v_mul_f32_e32 v169, v91, v91
	v_mul_f32_e32 v143, v90, v90
	v_mul_f32_e32 v145, v92, v92
	v_mul_f32_e32 v142, v93, v93
	v_add_f32_e32 v169, v169, v143
	v_add_f32_e32 v240, v145, v142
	v_add_f32_e32 v169, v169, v240
	v_add_f32_e32 v167, v167, v169
	v_add_u32_e32 v241, 0x100000, v159
	global_load_dwordx4 v[182:185], v241, s[14:15]
	global_load_dwordx4 v[186:189], v241, s[14:15] offset:64
	global_load_dwordx4 v[190:193], v241, s[14:15] offset:512
	global_load_dwordx4 v[194:197], v241, s[14:15] offset:576
	v_mov_b32_e32 v168, v167
	s_nop 1
	v_permlane16_swap_b32 v167, v168
	s_nop 1
	v_add_f32_e32 v167, v167, v168
	v_mov_b32_e32 v168, v167
	s_nop 1
	v_permlane32_swap_b32 v168, v167
	v_mov_b32_e32 v242, v160
	s_and_saveexec_b64 s[10:11], vcc
	v_add_f32_e32 v243, v168, v167
	global_store_dword v242, v243, s[22:23]
	s_or_b64 exec, exec, s[10:11]
	v_add_u32_e32 v161, 0x20000, v159
	v_lshrrev_b32_e32 v166, 1, v161
	s_waitcnt vmcnt(21)
; __device__ __forceinline__ unsigned cvt_pk_bf16(float lo, float hi) { unsigned r; asm volatile("v_cvt_pk_bf16_f32 %0, %1, %2" : "=v"(r) : "v"(lo), "v"(hi)); return r; }
;     __device__ __forceinline__ void operator()(const f32x4 (&acc)[2][2][4][2], const Unit& u, int wr, int wc, int fr, int fq) const {
;     ...
; #pragma unroll
;         for (int ai = 0; ai < 2; ++ai)
; #pragma unroll
;             for (int m = 0; m < 4; ++m) { const int row = u.pm * BM + ai * HALF + wr * 64 + m * 16 + fr; const int b = row >= 4224 ? 1 : 0, t = row - b * 4224; float ss = 0.f;
; #pragma unroll
;                 for (int bj = 0; bj < 2; ++bj)
; #pragma unroll
;                     for (int n = 0; n < 2; ++n) { const int col = u.pn * BM + bj * HALF + wc * 32 + n * 16 + 4 * fq; float* p = H + (size_t)row * 2048 + col;
;                         const f32x4 v = *(const f32x4*)p + acc[ai][bj][m][n] * s; *(f32x4*)p = v;
;                         if (SSQ != nullptr) { typedef unsigned u32x2 __attribute__((ext_vector_type(2))); u32x2 w; w.x = cvt_pk_bf16(v[0], v[1]); w.y = cvt_pk_bf16(v[2], v[3]); *(u32x2*)(HB + (size_t)row * 2048 + col) = w;
;                             ss += (v[0] * v[0] + v[1] * v[1]) + (v[2] * v[2] + v[3] * v[3]); }
;                         if (OUT != 0ull && t >= 128) *(__attribute__((address_space(1))) f32x4*)(OUT + ((size_t)(b * 4096 + t - 128) * 2048 + col) * 4) = v; }
;                 if (SSQ != nullptr) {
;                     { float p0 = ss, p1 = ss; asm("s_nop 1\n\tv_permlane16_swap_b32 %0, %1" : "+v"(p0), "+v"(p1)); ss = p0 + p1; p0 = ss; p1 = ss; asm("s_nop 1\n\tv_permlane32_swap_b32 %0, %1" : "+v"(p0), "+v"(p1)); ss = p0 + p1; }
;                     if (fq == 0) SSQ[(size_t)row * 32 + 4 * u.pn + wc] = ss; }
;                 asm volatile("" ::: "memory"); }
	v_pk_fma_f32 v[120:121], v[120:121], 0.5, v[200:201] op_sel_hi:[1,0,1]
	v_pk_fma_f32 v[118:119], v[118:119], 0.5, v[198:199] op_sel_hi:[1,0,1]
	global_store_dwordx4 v161, v[118:121], s[14:15]
	v_cvt_pk_bf16_f32 v244, v118, v119
	v_cvt_pk_bf16_f32 v245, v120, v121
	global_store_dwordx2 v166, v[244:245], s[20:21]
	v_mul_f32_e32 v167, v119, v119
	v_mul_f32_e32 v143, v118, v118
	v_mul_f32_e32 v145, v120, v120
	v_mul_f32_e32 v142, v121, v121
	v_add_f32_e32 v167, v167, v143
	v_add_f32_e32 v240, v145, v142
	v_add_f32_e32 v167, v167, v240
	v_pk_fma_f32 v[116:117], v[116:117], 0.5, v[204:205] op_sel_hi:[1,0,1]
	v_pk_fma_f32 v[114:115], v[114:115], 0.5, v[202:203] op_sel_hi:[1,0,1]
	global_store_dwordx4 v161, v[114:117], s[14:15] offset:64
	v_cvt_pk_bf16_f32 v244, v114, v115
	v_cvt_pk_bf16_f32 v245, v116, v117
	global_store_dwordx2 v166, v[244:245], s[20:21] offset:32
	v_mul_f32_e32 v169, v115, v115
	v_mul_f32_e32 v143, v114, v114
	v_mul_f32_e32 v145, v116, v116
	v_mul_f32_e32 v142, v117, v117
	v_add_f32_e32 v169, v169, v143
	v_add_f32_e32 v240, v145, v142
	v_add_f32_e32 v169, v169, v240
	v_add_f32_e32 v167, v167, v169
	v_pk_fma_f32 v[88:89], v[88:89], 0.5, v[208:209] op_sel_hi:[1,0,1]
	v_pk_fma_f32 v[86:87], v[86:87], 0.5, v[206:207] op_sel_hi:[1,0,1]
	global_store_dwordx4 v161, v[86:89], s[14:15] offset:512
	v_cvt_pk_bf16_f32 v244, v86, v87
	v_cvt_pk_bf16_f32 v245, v88, v89
	global_store_dwordx2 v166, v[244:245], s[20:21] offset:256
	v_mul_f32_e32 v169, v87, v87
	v_mul_f32_e32 v143, v86, v86
	v_mul_f32_e32 v145, v88, v88
	v_mul_f32_e32 v142, v89, v89
	v_add_f32_e32 v169, v169, v143
	v_add_f32_e32 v240, v145, v142
	v_add_f32_e32 v169, v169, v240
	v_add_f32_e32 v167, v167, v169
	v_pk_fma_f32 v[84:85], v[84:85], 0.5, v[212:213] op_sel_hi:[1,0,1]
	v_pk_fma_f32 v[82:83], v[82:83], 0.5, v[210:211] op_sel_hi:[1,0,1]
	global_store_dwordx4 v161, v[82:85], s[14:15] offset:576
	v_cvt_pk_bf16_f32 v244, v82, v83
	v_cvt_pk_bf16_f32 v245, v84, v85
	global_store_dwordx2 v166, v[244:245], s[20:21] offset:288
	v_mul_f32_e32 v169, v83, v83
	v_mul_f32_e32 v143, v82, v82
	v_mul_f32_e32 v145, v84, v84
	v_mul_f32_e32 v142, v85, v85
	v_add_f32_e32 v169, v169, v143
	v_add_f32_e32 v240, v145, v142
	v_add_f32_e32 v169, v169, v240
	v_add_f32_e32 v167, v167, v169
	v_add_u32_e32 v241, 0x120000, v159
	global_load_dwordx4 v[198:201], v241, s[14:15]
	global_load_dwordx4 v[202:205], v241, s[14:15] offset:64
	global_load_dwordx4 v[206:209], v241, s[14:15] offset:512
	global_load_dwordx4 v[210:213], v241, s[14:15] offset:576
	v_mov_b32_e32 v168, v167
	s_nop 1
	v_permlane16_swap_b32 v167, v168
	s_nop 1
	v_add_f32_e32 v167, v167, v168
	v_mov_b32_e32 v168, v167
	s_nop 1
	v_permlane32_swap_b32 v168, v167
	v_add_u32_e32 v242, 0x800, v160
	s_and_saveexec_b64 s[10:11], vcc
	v_add_f32_e32 v243, v168, v167
	global_store_dword v242, v243, s[22:23]
	s_or_b64 exec, exec, s[10:11]
	v_add_u32_e32 v161, 0x40000, v159
	v_lshrrev_b32_e32 v166, 1, v161
	s_waitcnt vmcnt(30)
	v_pk_fma_f32 v[112:113], v[112:113], 0.5, v[216:217] op_sel_hi:[1,0,1]
	v_pk_fma_f32 v[110:111], v[110:111], 0.5, v[214:215] op_sel_hi:[1,0,1]
	global_store_dwordx4 v161, v[110:113], s[14:15]
	v_cvt_pk_bf16_f32 v244, v110, v111
	v_cvt_pk_bf16_f32 v245, v112, v113
	global_store_dwordx2 v166, v[244:245], s[20:21]
	v_mul_f32_e32 v167, v111, v111
	v_mul_f32_e32 v143, v110, v110
	v_mul_f32_e32 v145, v112, v112
	v_mul_f32_e32 v142, v113, v113
	v_add_f32_e32 v167, v167, v143
	v_add_f32_e32 v240, v145, v142
	v_add_f32_e32 v167, v167, v240
	v_pk_fma_f32 v[108:109], v[108:109], 0.5, v[220:221] op_sel_hi:[1,0,1]
	v_pk_fma_f32 v[106:107], v[106:107], 0.5, v[218:219] op_sel_hi:[1,0,1]
	global_store_dwordx4 v161, v[106:109], s[14:15] offset:64
	v_cvt_pk_bf16_f32 v244, v106, v107
	v_cvt_pk_bf16_f32 v245, v108, v109
	global_store_dwordx2 v166, v[244:245], s[20:21] offset:32
	v_mul_f32_e32 v169, v107, v107
	v_mul_f32_e32 v143, v106, v106
	v_mul_f32_e32 v145, v108, v108
	v_mul_f32_e32 v142, v109, v109
	v_add_f32_e32 v169, v169, v143
	v_add_f32_e32 v240, v145, v142
	v_add_f32_e32 v169, v169, v240
	v_add_f32_e32 v167, v167, v169
	v_pk_fma_f32 v[80:81], v[80:81], 0.5, v[224:225] op_sel_hi:[1,0,1]
	v_pk_fma_f32 v[78:79], v[78:79], 0.5, v[222:223] op_sel_hi:[1,0,1]
	global_store_dwordx4 v161, v[78:81], s[14:15] offset:512
	v_cvt_pk_bf16_f32 v244, v78, v79
	v_cvt_pk_bf16_f32 v245, v80, v81
	global_store_dwordx2 v166, v[244:245], s[20:21] offset:256
	v_mul_f32_e32 v169, v79, v79
	v_mul_f32_e32 v143, v78, v78
	v_mul_f32_e32 v145, v80, v80
	v_mul_f32_e32 v142, v81, v81
	v_add_f32_e32 v169, v169, v143
	v_add_f32_e32 v240, v145, v142
	v_add_f32_e32 v169, v169, v240
	v_add_f32_e32 v167, v167, v169
	v_pk_fma_f32 v[76:77], v[76:77], 0.5, v[228:229] op_sel_hi:[1,0,1]
	v_pk_fma_f32 v[74:75], v[74:75], 0.5, v[226:227] op_sel_hi:[1,0,1]
	global_store_dwordx4 v161, v[74:77], s[14:15] offset:576
	v_cvt_pk_bf16_f32 v244, v74, v75
	v_cvt_pk_bf16_f32 v245, v76, v77
	global_store_dwordx2 v166, v[244:245], s[20:21] offset:288
	v_mul_f32_e32 v169, v75, v75
	v_mul_f32_e32 v143, v74, v74
	v_mul_f32_e32 v145, v76, v76
	v_mul_f32_e32 v142, v77, v77
	v_add_f32_e32 v169, v169, v143
	v_add_f32_e32 v240, v145, v142
	v_add_f32_e32 v169, v169, v240
	v_add_f32_e32 v167, v167, v169
	v_add_u32_e32 v241, 0x140000, v159
	global_load_dwordx4 v[214:217], v241, s[14:15]
	global_load_dwordx4 v[218:221], v241, s[14:15] offset:64
	global_load_dwordx4 v[222:225], v241, s[14:15] offset:512
	global_load_dwordx4 v[226:229], v241, s[14:15] offset:576
	v_mov_b32_e32 v168, v167
	s_nop 1
	v_permlane16_swap_b32 v167, v168
	s_nop 1
	v_add_f32_e32 v167, v167, v168
	v_mov_b32_e32 v168, v167
	s_nop 1
	v_permlane32_swap_b32 v168, v167
	v_add_u32_e32 v242, 0x1000, v160
	s_and_saveexec_b64 s[10:11], vcc
	v_add_f32_e32 v243, v168, v167
	global_store_dword v242, v243, s[22:23]
	s_or_b64 exec, exec, s[10:11]
	v_add_u32_e32 v161, 0x60000, v159
	v_lshrrev_b32_e32 v166, 1, v161
	s_waitcnt vmcnt(39)
; __device__ __forceinline__ unsigned cvt_pk_bf16(float lo, float hi) { unsigned r; asm volatile("v_cvt_pk_bf16_f32 %0, %1, %2" : "=v"(r) : "v"(lo), "v"(hi)); return r; }
;     __device__ __forceinline__ void operator()(const f32x4 (&acc)[2][2][4][2], const Unit& u, int wr, int wc, int fr, int fq) const {
;     ...
; #pragma unroll
;         for (int ai = 0; ai < 2; ++ai)
; #pragma unroll
;             for (int m = 0; m < 4; ++m) { const int row = u.pm * BM + ai * HALF + wr * 64 + m * 16 + fr; const int b = row >= 4224 ? 1 : 0, t = row - b * 4224; float ss = 0.f;
; #pragma unroll
;                 for (int bj = 0; bj < 2; ++bj)
; #pragma unroll
;                     for (int n = 0; n < 2; ++n) { const int col = u.pn * BM + bj * HALF + wc * 32 + n * 16 + 4 * fq; float* p = H + (size_t)row * 2048 + col;
;                         const f32x4 v = *(const f32x4*)p + acc[ai][bj][m][n] * s; *(f32x4*)p = v;
;                         if (SSQ != nullptr) { typedef unsigned u32x2 __attribute__((ext_vector_type(2))); u32x2 w; w.x = cvt_pk_bf16(v[0], v[1]); w.y = cvt_pk_bf16(v[2], v[3]); *(u32x2*)(HB + (size_t)row * 2048 + col) = w;
;                             ss += (v[0] * v[0] + v[1] * v[1]) + (v[2] * v[2] + v[3] * v[3]); }
;                         if (OUT != 0ull && t >= 128) *(__attribute__((address_space(1))) f32x4*)(OUT + ((size_t)(b * 4096 + t - 128) * 2048 + col) * 4) = v; }
;                 if (SSQ != nullptr) {
;                     { float p0 = ss, p1 = ss; asm("s_nop 1\n\tv_permlane16_swap_b32 %0, %1" : "+v"(p0), "+v"(p1)); ss = p0 + p1; p0 = ss; p1 = ss; asm("s_nop 1\n\tv_permlane32_swap_b32 %0, %1" : "+v"(p0), "+v"(p1)); ss = p0 + p1; }
;                     if (fq == 0) SSQ[(size_t)row * 32 + 4 * u.pn + wc] = ss; }
;                 asm volatile("" ::: "memory"); }
	v_pk_fma_f32 v[104:105], v[104:105], 0.5, v[148:149] op_sel_hi:[1,0,1]
	v_pk_fma_f32 v[102:103], v[102:103], 0.5, v[146:147] op_sel_hi:[1,0,1]
	global_store_dwordx4 v161, v[102:105], s[14:15]
	v_cvt_pk_bf16_f32 v244, v102, v103
	v_cvt_pk_bf16_f32 v245, v104, v105
	global_store_dwordx2 v166, v[244:245], s[20:21]
	v_mul_f32_e32 v167, v103, v103
	v_mul_f32_e32 v143, v102, v102
	v_mul_f32_e32 v145, v104, v104
	v_mul_f32_e32 v142, v105, v105
	v_add_f32_e32 v167, v167, v143
	v_add_f32_e32 v240, v145, v142
	v_add_f32_e32 v167, v167, v240
	v_pk_fma_f32 v[100:101], v[100:101], 0.5, v[152:153] op_sel_hi:[1,0,1]
	v_pk_fma_f32 v[98:99], v[98:99], 0.5, v[150:151] op_sel_hi:[1,0,1]
	global_store_dwordx4 v161, v[98:101], s[14:15] offset:64
	v_cvt_pk_bf16_f32 v244, v98, v99
	v_cvt_pk_bf16_f32 v245, v100, v101
	global_store_dwordx2 v166, v[244:245], s[20:21] offset:32
	v_mul_f32_e32 v169, v99, v99
	v_mul_f32_e32 v143, v98, v98
	v_mul_f32_e32 v145, v100, v100
	v_mul_f32_e32 v142, v101, v101
	v_add_f32_e32 v169, v169, v143
	v_add_f32_e32 v240, v145, v142
	v_add_f32_e32 v169, v169, v240
	v_add_f32_e32 v167, v167, v169
	v_pk_fma_f32 v[72:73], v[72:73], 0.5, v[156:157] op_sel_hi:[1,0,1]
	v_pk_fma_f32 v[70:71], v[70:71], 0.5, v[154:155] op_sel_hi:[1,0,1]
	global_store_dwordx4 v161, v[70:73], s[14:15] offset:512
	v_cvt_pk_bf16_f32 v244, v70, v71
	v_cvt_pk_bf16_f32 v245, v72, v73
	global_store_dwordx2 v166, v[244:245], s[20:21] offset:256
	v_mul_f32_e32 v169, v71, v71
	v_mul_f32_e32 v143, v70, v70
	v_mul_f32_e32 v145, v72, v72
	v_mul_f32_e32 v142, v73, v73
	v_add_f32_e32 v169, v169, v143
	v_add_f32_e32 v240, v145, v142
	v_add_f32_e32 v169, v169, v240
	v_add_f32_e32 v167, v167, v169
	v_pk_fma_f32 v[68:69], v[68:69], 0.5, v[132:133] op_sel_hi:[1,0,1]
	v_pk_fma_f32 v[66:67], v[66:67], 0.5, v[130:131] op_sel_hi:[1,0,1]
	global_store_dwordx4 v161, v[66:69], s[14:15] offset:576
	v_cvt_pk_bf16_f32 v244, v66, v67
	v_cvt_pk_bf16_f32 v245, v68, v69
	global_store_dwordx2 v166, v[244:245], s[20:21] offset:288
	v_mul_f32_e32 v169, v67, v67
	v_mul_f32_e32 v143, v66, v66
	v_mul_f32_e32 v145, v68, v68
	v_mul_f32_e32 v142, v69, v69
	v_add_f32_e32 v169, v169, v143
	v_add_f32_e32 v240, v145, v142
	v_add_f32_e32 v169, v169, v240
	v_add_f32_e32 v167, v167, v169
	v_add_u32_e32 v241, 0x160000, v159
	global_load_dwordx4 v[146:149], v241, s[14:15]
	global_load_dwordx4 v[150:153], v241, s[14:15] offset:64
	global_load_dwordx4 v[154:157], v241, s[14:15] offset:512
	global_load_dwordx4 v[130:133], v241, s[14:15] offset:576
	v_mov_b32_e32 v168, v167
	s_nop 1
	v_permlane16_swap_b32 v167, v168
	s_nop 1
	v_add_f32_e32 v167, v167, v168
	v_mov_b32_e32 v168, v167
	s_nop 1
	v_permlane32_swap_b32 v168, v167
	v_add_u32_e32 v242, 0x1800, v160
	s_and_saveexec_b64 s[10:11], vcc
	v_add_f32_e32 v243, v168, v167
	global_store_dword v242, v243, s[22:23]
	s_or_b64 exec, exec, s[10:11]
	v_add_u32_e32 v161, 0x100000, v159
	v_lshrrev_b32_e32 v166, 1, v161
	s_waitcnt vmcnt(40)
	v_pk_fma_f32 v[64:65], v[64:65], 0.5, v[184:185] op_sel_hi:[1,0,1]
	v_pk_fma_f32 v[62:63], v[62:63], 0.5, v[182:183] op_sel_hi:[1,0,1]
	global_store_dwordx4 v161, v[62:65], s[14:15]
	v_cvt_pk_bf16_f32 v244, v62, v63
	v_cvt_pk_bf16_f32 v245, v64, v65
	global_store_dwordx2 v166, v[244:245], s[20:21]
	v_mul_f32_e32 v167, v63, v63
	v_mul_f32_e32 v143, v62, v62
	v_mul_f32_e32 v145, v64, v64
	v_mul_f32_e32 v142, v65, v65
	v_add_f32_e32 v167, v167, v143
	v_add_f32_e32 v240, v145, v142
	v_add_f32_e32 v167, v167, v240
	v_pk_fma_f32 v[60:61], v[60:61], 0.5, v[188:189] op_sel_hi:[1,0,1]
	v_pk_fma_f32 v[58:59], v[58:59], 0.5, v[186:187] op_sel_hi:[1,0,1]
	global_store_dwordx4 v161, v[58:61], s[14:15] offset:64
	v_cvt_pk_bf16_f32 v244, v58, v59
	v_cvt_pk_bf16_f32 v245, v60, v61
	global_store_dwordx2 v166, v[244:245], s[20:21] offset:32
	v_mul_f32_e32 v169, v59, v59
	v_mul_f32_e32 v143, v58, v58
	v_mul_f32_e32 v145, v60, v60
	v_mul_f32_e32 v142, v61, v61
	v_add_f32_e32 v169, v169, v143
	v_add_f32_e32 v240, v145, v142
	v_add_f32_e32 v169, v169, v240
	v_add_f32_e32 v167, v167, v169
	v_pk_fma_f32 v[32:33], v[32:33], 0.5, v[192:193] op_sel_hi:[1,0,1]
	v_pk_fma_f32 v[30:31], v[30:31], 0.5, v[190:191] op_sel_hi:[1,0,1]
	global_store_dwordx4 v161, v[30:33], s[14:15] offset:512
	v_cvt_pk_bf16_f32 v244, v30, v31
	v_cvt_pk_bf16_f32 v245, v32, v33
	global_store_dwordx2 v166, v[244:245], s[20:21] offset:256
	v_mul_f32_e32 v169, v31, v31
	v_mul_f32_e32 v143, v30, v30
	v_mul_f32_e32 v145, v32, v32
	v_mul_f32_e32 v142, v33, v33
	v_add_f32_e32 v169, v169, v143
	v_add_f32_e32 v240, v145, v142
	v_add_f32_e32 v169, v169, v240
	v_add_f32_e32 v167, v167, v169
	v_pk_fma_f32 v[28:29], v[28:29], 0.5, v[196:197] op_sel_hi:[1,0,1]
	v_pk_fma_f32 v[26:27], v[26:27], 0.5, v[194:195] op_sel_hi:[1,0,1]
	global_store_dwordx4 v161, v[26:29], s[14:15] offset:576
	v_cvt_pk_bf16_f32 v244, v26, v27
	v_cvt_pk_bf16_f32 v245, v28, v29
	global_store_dwordx2 v166, v[244:245], s[20:21] offset:288
	v_mul_f32_e32 v169, v27, v27
	v_mul_f32_e32 v143, v26, v26
	v_mul_f32_e32 v145, v28, v28
	v_mul_f32_e32 v142, v29, v29
	v_add_f32_e32 v169, v169, v143
	v_add_f32_e32 v240, v145, v142
	v_add_f32_e32 v169, v169, v240
	v_add_f32_e32 v167, v167, v169
	v_mov_b32_e32 v168, v167
	s_nop 1
	v_permlane16_swap_b32 v167, v168
	s_nop 1
	v_add_f32_e32 v167, v167, v168
	v_mov_b32_e32 v168, v167
	s_nop 1
	v_permlane32_swap_b32 v168, v167
	v_add_u32_e32 v242, 0x4000, v160
	s_and_saveexec_b64 s[10:11], vcc
	v_add_f32_e32 v243, v168, v167
	global_store_dword v242, v243, s[22:23]
	s_or_b64 exec, exec, s[10:11]
	v_add_u32_e32 v161, 0x120000, v159
	v_lshrrev_b32_e32 v166, 1, v161
	s_waitcnt vmcnt(36)
; __device__ __forceinline__ unsigned cvt_pk_bf16(float lo, float hi) { unsigned r; asm volatile("v_cvt_pk_bf16_f32 %0, %1, %2" : "=v"(r) : "v"(lo), "v"(hi)); return r; }
;     __device__ __forceinline__ void operator()(const f32x4 (&acc)[2][2][4][2], const Unit& u, int wr, int wc, int fr, int fq) const {
;     ...
; #pragma unroll
;         for (int ai = 0; ai < 2; ++ai)
; #pragma unroll
;             for (int m = 0; m < 4; ++m) { const int row = u.pm * BM + ai * HALF + wr * 64 + m * 16 + fr; const int b = row >= 4224 ? 1 : 0, t = row - b * 4224; float ss = 0.f;
; #pragma unroll
;                 for (int bj = 0; bj < 2; ++bj)
; #pragma unroll
;                     for (int n = 0; n < 2; ++n) { const int col = u.pn * BM + bj * HALF + wc * 32 + n * 16 + 4 * fq; float* p = H + (size_t)row * 2048 + col;
;                         const f32x4 v = *(const f32x4*)p + acc[ai][bj][m][n] * s; *(f32x4*)p = v;
;                         if (SSQ != nullptr) { typedef unsigned u32x2 __attribute__((ext_vector_type(2))); u32x2 w; w.x = cvt_pk_bf16(v[0], v[1]); w.y = cvt_pk_bf16(v[2], v[3]); *(u32x2*)(HB + (size_t)row * 2048 + col) = w;
;                             ss += (v[0] * v[0] + v[1] * v[1]) + (v[2] * v[2] + v[3] * v[3]); }
;                         if (OUT != 0ull && t >= 128) *(__attribute__((address_space(1))) f32x4*)(OUT + ((size_t)(b * 4096 + t - 128) * 2048 + col) * 4) = v; }
;                 if (SSQ != nullptr) {
;                     { float p0 = ss, p1 = ss; asm("s_nop 1\n\tv_permlane16_swap_b32 %0, %1" : "+v"(p0), "+v"(p1)); ss = p0 + p1; p0 = ss; p1 = ss; asm("s_nop 1\n\tv_permlane32_swap_b32 %0, %1" : "+v"(p0), "+v"(p1)); ss = p0 + p1; }
;                     if (fq == 0) SSQ[(size_t)row * 32 + 4 * u.pn + wc] = ss; }
;                 asm volatile("" ::: "memory"); }
	v_pk_fma_f32 v[56:57], v[56:57], 0.5, v[200:201] op_sel_hi:[1,0,1]
	v_pk_fma_f32 v[54:55], v[54:55], 0.5, v[198:199] op_sel_hi:[1,0,1]
	global_store_dwordx4 v161, v[54:57], s[14:15]
	v_cvt_pk_bf16_f32 v244, v54, v55
	v_cvt_pk_bf16_f32 v245, v56, v57
	global_store_dwordx2 v166, v[244:245], s[20:21]
	v_mul_f32_e32 v167, v55, v55
	v_mul_f32_e32 v143, v54, v54
	v_mul_f32_e32 v145, v56, v56
	v_mul_f32_e32 v142, v57, v57
	v_add_f32_e32 v167, v167, v143
	v_add_f32_e32 v240, v145, v142
	v_add_f32_e32 v167, v167, v240
	v_pk_fma_f32 v[52:53], v[52:53], 0.5, v[204:205] op_sel_hi:[1,0,1]
	v_pk_fma_f32 v[50:51], v[50:51], 0.5, v[202:203] op_sel_hi:[1,0,1]
	global_store_dwordx4 v161, v[50:53], s[14:15] offset:64
	v_cvt_pk_bf16_f32 v244, v50, v51
	v_cvt_pk_bf16_f32 v245, v52, v53
	global_store_dwordx2 v166, v[244:245], s[20:21] offset:32
	v_mul_f32_e32 v169, v51, v51
	v_mul_f32_e32 v143, v50, v50
	v_mul_f32_e32 v145, v52, v52
	v_mul_f32_e32 v142, v53, v53
	v_add_f32_e32 v169, v169, v143
	v_add_f32_e32 v240, v145, v142
	v_add_f32_e32 v169, v169, v240
	v_add_f32_e32 v167, v167, v169
	v_pk_fma_f32 v[24:25], v[24:25], 0.5, v[208:209] op_sel_hi:[1,0,1]
	v_pk_fma_f32 v[22:23], v[22:23], 0.5, v[206:207] op_sel_hi:[1,0,1]
	global_store_dwordx4 v161, v[22:25], s[14:15] offset:512
	v_cvt_pk_bf16_f32 v244, v22, v23
	v_cvt_pk_bf16_f32 v245, v24, v25
	global_store_dwordx2 v166, v[244:245], s[20:21] offset:256
	v_mul_f32_e32 v169, v23, v23
	v_mul_f32_e32 v143, v22, v22
	v_mul_f32_e32 v145, v24, v24
	v_mul_f32_e32 v142, v25, v25
	v_add_f32_e32 v169, v169, v143
	v_add_f32_e32 v240, v145, v142
	v_add_f32_e32 v169, v169, v240
	v_add_f32_e32 v167, v167, v169
	v_pk_fma_f32 v[20:21], v[20:21], 0.5, v[212:213] op_sel_hi:[1,0,1]
	v_pk_fma_f32 v[18:19], v[18:19], 0.5, v[210:211] op_sel_hi:[1,0,1]
	global_store_dwordx4 v161, v[18:21], s[14:15] offset:576
	v_cvt_pk_bf16_f32 v244, v18, v19
	v_cvt_pk_bf16_f32 v245, v20, v21
	global_store_dwordx2 v166, v[244:245], s[20:21] offset:288
	v_mul_f32_e32 v169, v19, v19
	v_mul_f32_e32 v143, v18, v18
	v_mul_f32_e32 v145, v20, v20
	v_mul_f32_e32 v142, v21, v21
	v_add_f32_e32 v169, v169, v143
	v_add_f32_e32 v240, v145, v142
	v_add_f32_e32 v169, v169, v240
	v_add_f32_e32 v167, v167, v169
	v_mov_b32_e32 v168, v167
	s_nop 1
	v_permlane16_swap_b32 v167, v168
	s_nop 1
	v_add_f32_e32 v167, v167, v168
	v_mov_b32_e32 v168, v167
	s_nop 1
	v_permlane32_swap_b32 v168, v167
	v_add_u32_e32 v242, 0x4800, v160
	s_and_saveexec_b64 s[10:11], vcc
	v_add_f32_e32 v243, v168, v167
	global_store_dword v242, v243, s[22:23]
	s_or_b64 exec, exec, s[10:11]
	v_add_u32_e32 v161, 0x140000, v159
	v_lshrrev_b32_e32 v166, 1, v161
	s_waitcnt vmcnt(32)
	v_pk_fma_f32 v[48:49], v[48:49], 0.5, v[216:217] op_sel_hi:[1,0,1]
	v_pk_fma_f32 v[46:47], v[46:47], 0.5, v[214:215] op_sel_hi:[1,0,1]
	global_store_dwordx4 v161, v[46:49], s[14:15]
	v_cvt_pk_bf16_f32 v244, v46, v47
	v_cvt_pk_bf16_f32 v245, v48, v49
	global_store_dwordx2 v166, v[244:245], s[20:21]
	v_mul_f32_e32 v167, v47, v47
	v_mul_f32_e32 v143, v46, v46
	v_mul_f32_e32 v145, v48, v48
	v_mul_f32_e32 v142, v49, v49
	v_add_f32_e32 v167, v167, v143
	v_add_f32_e32 v240, v145, v142
	v_add_f32_e32 v167, v167, v240
	v_pk_fma_f32 v[44:45], v[44:45], 0.5, v[220:221] op_sel_hi:[1,0,1]
	v_pk_fma_f32 v[42:43], v[42:43], 0.5, v[218:219] op_sel_hi:[1,0,1]
	global_store_dwordx4 v161, v[42:45], s[14:15] offset:64
	v_cvt_pk_bf16_f32 v244, v42, v43
	v_cvt_pk_bf16_f32 v245, v44, v45
	global_store_dwordx2 v166, v[244:245], s[20:21] offset:32
	v_mul_f32_e32 v169, v43, v43
	v_mul_f32_e32 v143, v42, v42
	v_mul_f32_e32 v145, v44, v44
	v_mul_f32_e32 v142, v45, v45
	v_add_f32_e32 v169, v169, v143
	v_add_f32_e32 v240, v145, v142
	v_add_f32_e32 v169, v169, v240
	v_add_f32_e32 v167, v167, v169
	v_pk_fma_f32 v[16:17], v[16:17], 0.5, v[224:225] op_sel_hi:[1,0,1]
	v_pk_fma_f32 v[14:15], v[14:15], 0.5, v[222:223] op_sel_hi:[1,0,1]
	global_store_dwordx4 v161, v[14:17], s[14:15] offset:512
	v_cvt_pk_bf16_f32 v244, v14, v15
	v_cvt_pk_bf16_f32 v245, v16, v17
	global_store_dwordx2 v166, v[244:245], s[20:21] offset:256
	v_mul_f32_e32 v169, v15, v15
	v_mul_f32_e32 v143, v14, v14
	v_mul_f32_e32 v145, v16, v16
	v_mul_f32_e32 v142, v17, v17
	v_add_f32_e32 v169, v169, v143
	v_add_f32_e32 v240, v145, v142
	v_add_f32_e32 v169, v169, v240
	v_add_f32_e32 v167, v167, v169
	v_pk_fma_f32 v[12:13], v[12:13], 0.5, v[228:229] op_sel_hi:[1,0,1]
	v_pk_fma_f32 v[10:11], v[10:11], 0.5, v[226:227] op_sel_hi:[1,0,1]
	global_store_dwordx4 v161, v[10:13], s[14:15] offset:576
	v_cvt_pk_bf16_f32 v244, v10, v11
	v_cvt_pk_bf16_f32 v245, v12, v13
	global_store_dwordx2 v166, v[244:245], s[20:21] offset:288
	v_mul_f32_e32 v169, v11, v11
	v_mul_f32_e32 v143, v10, v10
	v_mul_f32_e32 v145, v12, v12
	v_mul_f32_e32 v142, v13, v13
	v_add_f32_e32 v169, v169, v143
	v_add_f32_e32 v240, v145, v142
	v_add_f32_e32 v169, v169, v240
	v_add_f32_e32 v167, v167, v169
	v_mov_b32_e32 v168, v167
	s_nop 1
	v_permlane16_swap_b32 v167, v168
	s_nop 1
	v_add_f32_e32 v167, v167, v168
	v_mov_b32_e32 v168, v167
	s_nop 1
	v_permlane32_swap_b32 v168, v167
	v_add_u32_e32 v242, 0x5000, v160
	s_and_saveexec_b64 s[10:11], vcc
	v_add_f32_e32 v243, v168, v167
	global_store_dword v242, v243, s[22:23]
	s_or_b64 exec, exec, s[10:11]
	v_add_u32_e32 v161, 0x160000, v159
	v_lshrrev_b32_e32 v166, 1, v161
	s_waitcnt vmcnt(28)
; __device__ __forceinline__ unsigned cvt_pk_bf16(float lo, float hi) { unsigned r; asm volatile("v_cvt_pk_bf16_f32 %0, %1, %2" : "=v"(r) : "v"(lo), "v"(hi)); return r; }
;     __device__ __forceinline__ void operator()(const f32x4 (&acc)[2][2][4][2], const Unit& u, int wr, int wc, int fr, int fq) const {
;     ...
; #pragma unroll
;         for (int ai = 0; ai < 2; ++ai)
; #pragma unroll
;             for (int m = 0; m < 4; ++m) { const int row = u.pm * BM + ai * HALF + wr * 64 + m * 16 + fr; const int b = row >= 4224 ? 1 : 0, t = row - b * 4224; float ss = 0.f;
; #pragma unroll
;                 for (int bj = 0; bj < 2; ++bj)
; #pragma unroll
;                     for (int n = 0; n < 2; ++n) { const int col = u.pn * BM + bj * HALF + wc * 32 + n * 16 + 4 * fq; float* p = H + (size_t)row * 2048 + col;
;                         const f32x4 v = *(const f32x4*)p + acc[ai][bj][m][n] * s; *(f32x4*)p = v;
;                         if (SSQ != nullptr) { typedef unsigned u32x2 __attribute__((ext_vector_type(2))); u32x2 w; w.x = cvt_pk_bf16(v[0], v[1]); w.y = cvt_pk_bf16(v[2], v[3]); *(u32x2*)(HB + (size_t)row * 2048 + col) = w;
;                             ss += (v[0] * v[0] + v[1] * v[1]) + (v[2] * v[2] + v[3] * v[3]); }
;                         if (OUT != 0ull && t >= 128) *(__attribute__((address_space(1))) f32x4*)(OUT + ((size_t)(b * 4096 + t - 128) * 2048 + col) * 4) = v; }
;                 if (SSQ != nullptr) {
;                     { float p0 = ss, p1 = ss; asm("s_nop 1\n\tv_permlane16_swap_b32 %0, %1" : "+v"(p0), "+v"(p1)); ss = p0 + p1; p0 = ss; p1 = ss; asm("s_nop 1\n\tv_permlane32_swap_b32 %0, %1" : "+v"(p0), "+v"(p1)); ss = p0 + p1; }
;                     if (fq == 0) SSQ[(size_t)row * 32 + 4 * u.pn + wc] = ss; }
;                 asm volatile("" ::: "memory"); }
	v_pk_fma_f32 v[40:41], v[40:41], 0.5, v[148:149] op_sel_hi:[1,0,1]
	v_pk_fma_f32 v[38:39], v[38:39], 0.5, v[146:147] op_sel_hi:[1,0,1]
	global_store_dwordx4 v161, v[38:41], s[14:15]
	v_cvt_pk_bf16_f32 v244, v38, v39
	v_cvt_pk_bf16_f32 v245, v40, v41
	global_store_dwordx2 v166, v[244:245], s[20:21]
	v_mul_f32_e32 v167, v39, v39
	v_mul_f32_e32 v143, v38, v38
	v_mul_f32_e32 v145, v40, v40
	v_mul_f32_e32 v142, v41, v41
	v_add_f32_e32 v167, v167, v143
	v_add_f32_e32 v240, v145, v142
	v_add_f32_e32 v167, v167, v240
	v_pk_fma_f32 v[36:37], v[36:37], 0.5, v[152:153] op_sel_hi:[1,0,1]
	v_pk_fma_f32 v[34:35], v[34:35], 0.5, v[150:151] op_sel_hi:[1,0,1]
	global_store_dwordx4 v161, v[34:37], s[14:15] offset:64
	v_cvt_pk_bf16_f32 v244, v34, v35
	v_cvt_pk_bf16_f32 v245, v36, v37
	global_store_dwordx2 v166, v[244:245], s[20:21] offset:32
	v_mul_f32_e32 v169, v35, v35
	v_mul_f32_e32 v143, v34, v34
	v_mul_f32_e32 v145, v36, v36
	v_mul_f32_e32 v142, v37, v37
	v_add_f32_e32 v169, v169, v143
	v_add_f32_e32 v240, v145, v142
	v_add_f32_e32 v169, v169, v240
	v_add_f32_e32 v167, v167, v169
	v_pk_fma_f32 v[8:9], v[8:9], 0.5, v[156:157] op_sel_hi:[1,0,1]
	v_pk_fma_f32 v[6:7], v[6:7], 0.5, v[154:155] op_sel_hi:[1,0,1]
	global_store_dwordx4 v161, v[6:9], s[14:15] offset:512
	v_cvt_pk_bf16_f32 v244, v6, v7
	v_cvt_pk_bf16_f32 v245, v8, v9
	global_store_dwordx2 v166, v[244:245], s[20:21] offset:256
	v_mul_f32_e32 v169, v7, v7
	v_mul_f32_e32 v143, v6, v6
	v_mul_f32_e32 v145, v8, v8
	v_mul_f32_e32 v142, v9, v9
	v_add_f32_e32 v169, v169, v143
	v_add_f32_e32 v240, v145, v142
	v_add_f32_e32 v169, v169, v240
	v_add_f32_e32 v167, v167, v169
	v_pk_fma_f32 v[4:5], v[4:5], 0.5, v[132:133] op_sel_hi:[1,0,1]
	v_pk_fma_f32 v[2:3], v[2:3], 0.5, v[130:131] op_sel_hi:[1,0,1]
	global_store_dwordx4 v161, v[2:5], s[14:15] offset:576
	v_cvt_pk_bf16_f32 v244, v2, v3
	v_cvt_pk_bf16_f32 v245, v4, v5
	global_store_dwordx2 v166, v[244:245], s[20:21] offset:288
	v_mul_f32_e32 v169, v3, v3
	v_mul_f32_e32 v143, v2, v2
	v_mul_f32_e32 v145, v4, v4
	v_mul_f32_e32 v142, v5, v5
	v_add_f32_e32 v169, v169, v143
	v_add_f32_e32 v240, v145, v142
	v_add_f32_e32 v169, v169, v240
	v_add_f32_e32 v167, v167, v169
	v_mov_b32_e32 v168, v167
	s_nop 1
	v_permlane16_swap_b32 v167, v168
	s_nop 1
	v_add_f32_e32 v167, v167, v168
	v_mov_b32_e32 v168, v167
	s_nop 1
	v_permlane32_swap_b32 v168, v167
	v_add_u32_e32 v242, 0x5800, v160
	s_and_saveexec_b64 s[10:11], vcc
	v_add_f32_e32 v243, v168, v167
	global_store_dword v242, v243, s[22:23]
	s_or_b64 exec, exec, s[10:11]
	s_branch .LBB0_1744
.Lnepi_slow:
	v_lshlrev_b64 v[130:131], 13, v[144:145]
	v_lshl_add_u64 v[130:131], s[14:15], 0, v[130:131]
	v_ashrrev_i32_e32 v143, 31, v142
	v_lshl_add_u64 v[152:153], v[142:143], 2, v[130:131]
	global_load_dwordx4 v[130:133], v[152:153], off
	v_lshlrev_b64 v[146:147], 11, v[144:145]
	v_mov_b32_e32 v159, 0
	s_and_b64 vcc, exec, s[16:17]
	v_lshl_add_u64 v[154:155], v[146:147], 1, s[20:21]
	s_waitcnt vmcnt(0)
	v_pk_fma_f32 v[132:133], v[128:129], 0.5, v[132:133] op_sel_hi:[1,0,1]
	v_pk_fma_f32 v[130:131], v[126:127], 0.5, v[130:131] op_sel_hi:[1,0,1]
	global_store_dwordx4 v[152:153], v[130:133], off
	s_cbranch_vccz .LBB0_1586
	v_cvt_pk_bf16_f32 v146, v130, v131
	v_cvt_pk_bf16_f32 v147, v132, v133
	v_lshl_add_u64 v[148:149], v[142:143], 1, v[154:155]
	global_store_dwordx2 v[148:149], v[146:147], off
	v_pk_mul_f32 v[146:147], v[132:133], v[132:133]
	v_pk_mul_f32 v[148:149], v[130:131], v[130:131]
	s_nop 0
	v_pk_mov_b32 v[150:151], v[148:149], v[146:147] op_sel:[1,0]
	v_mov_b32_e32 v149, v147
	v_pk_add_f32 v[146:147], v[150:151], v[148:149]
	s_nop 0
	v_add_f32_e32 v159, v146, v147
